# attention: removed compiler-inserted mid-tile vmcnt(0) before V tr-reads (next-tile DMA no longer waited before PV)
# baseline (speedup 1.0000x reference)
; __device__ __forceinline__ unsigned pk2(float lo, float hi) { f32x2_t v = {lo, hi}; bf16x2_t b = __builtin_convertvector(v, bf16x2_t); return __builtin_bit_cast(unsigned, b); }
; __device__ __forceinline__ v4i16_t lds_tr(LAS const unsigned char* p) { return __builtin_amdgcn_ds_read_tr16_b64_v4i16((LAS v4i16_t*)p); }
; __device__ __forceinline__ void attn_phase(const Ptrs& P, LAS unsigned char* lds, int vcu) {
;     ...
;                 float ls = 0.f;
; #pragma unroll
;                 for (int s = 0; s < 4; ++s) {
;                     float e[8];
; #pragma unroll
;                     for (int j = 0; j < 8; ++j) { e[j] = __builtin_amdgcn_exp2f(s < 2 ? p0[8 * (s & 1) + j] : p1[8 * (s & 1) + j]); }
;                     ls += ((e[0] + e[1]) + (e[2] + e[3])) + ((e[4] + e[5]) + (e[6] + e[7]));
;                     u32x4 pw; pw.x = pk2(e[0], e[1]); pw.y = pk2(e[2], e[3]); pw.z = pk2(e[4], e[5]); pw.w = pk2(e[6], e[7]);
;                     const bf16x8 pb = __builtin_bit_cast(bf16x8, pw);
; #pragma unroll
;                     for (int d = 0; d < 4; ++d) {
;                         const v4i16_t lo = lds_tr(st + vb + ((2 * s) * 4 + d) * 512), hv = lds_tr(st + vb + ((2 * s + 1) * 4 + d) * 512);
;                         const bf16x8 va = {lo[0], lo[1], lo[2], lo[3], hv[0], hv[1], hv[2], hv[3]};
;                         o[d] = __builtin_amdgcn_mfma_f32_32x32x16_bf16(va, pb, o[d], 0, 0, 0);
;                     }
;                 }
;                 lrun += ls;
.LBB0_1228:
	v_add_u32_e32 v0, s70, v215
	v_add3_u32 v11, v0, v177, v216
	v_exp_f32_e32 v2, v112
	v_exp_f32_e32 v6, v113
	v_exp_f32_e32 v4, v114
	v_exp_f32_e32 v8, v115
	v_exp_f32_e32 v3, v116
	v_exp_f32_e32 v7, v117
	v_exp_f32_e32 v5, v118
	v_exp_f32_e32 v9, v119
	ds_read_b64_tr_b16 v[112:113], v11 offset:24576
	ds_read_b64_tr_b16 v[114:115], v11 offset:26624
	ds_read_b64_tr_b16 v[116:117], v11 offset:25088
	ds_read_b64_tr_b16 v[226:227], v11 offset:25600
	ds_read_b64_tr_b16 v[230:231], v11 offset:26112
	ds_read_b64_tr_b16 v[118:119], v11 offset:27136
	ds_read_b64_tr_b16 v[228:229], v11 offset:27648
	ds_read_b64_tr_b16 v[232:233], v11 offset:28160
	v_cvt_pk_bf16_f32 v12, v2, v6
	v_cvt_pk_bf16_f32 v13, v4, v8
	v_cvt_pk_bf16_f32 v14, v3, v7
	v_cvt_pk_bf16_f32 v15, v5, v9
	v_exp_f32_e32 v225, v97
	v_exp_f32_e32 v234, v98
	s_waitcnt lgkmcnt(6)
	v_mfma_f32_32x32x16_bf16 v[64:79], v[112:115], v[12:15], v[64:79]
	ds_read_b64_tr_b16 v[112:113], v11 offset:28672
	ds_read_b64_tr_b16 v[114:115], v11 offset:30720
	v_exp_f32_e32 v235, v99
	v_exp_f32_e32 v236, v103
	v_pk_add_f32 v[2:3], v[2:3], v[6:7]
	v_pk_add_f32 v[4:5], v[4:5], v[8:9]
	v_exp_f32_e32 v104, v104
	v_pk_add_f32 v[2:3], v[2:3], v[4:5]
	s_waitcnt lgkmcnt(4)
	v_mfma_f32_32x32x16_bf16 v[48:63], v[116:119], v[12:15], v[48:63]
	v_exp_f32_e32 v106, v106
	v_exp_f32_e32 v0, v111
	s_waitcnt lgkmcnt(3)
	v_mfma_f32_32x32x16_bf16 v[32:47], v[226:229], v[12:15], v[32:47]
	v_exp_f32_e32 v226, v120
	v_exp_f32_e32 v228, v121
	v_exp_f32_e32 v227, v122
	v_exp_f32_e32 v229, v123
	s_waitcnt lgkmcnt(2)
	v_mfma_f32_32x32x16_bf16 v[16:31], v[230:233], v[12:15], v[16:31]
	v_exp_f32_e32 v230, v124
	v_exp_f32_e32 v232, v125
	v_exp_f32_e32 v231, v126
	v_exp_f32_e32 v233, v127
	ds_read_b64_tr_b16 v[116:117], v11 offset:29184
	ds_read_b64_tr_b16 v[120:121], v11 offset:29696
	ds_read_b64_tr_b16 v[124:125], v11 offset:30208
	ds_read_b64_tr_b16 v[118:119], v11 offset:31232
	ds_read_b64_tr_b16 v[122:123], v11 offset:31744
	ds_read_b64_tr_b16 v[126:127], v11 offset:32256
	v_cvt_pk_bf16_f32 v12, v226, v228
	v_cvt_pk_bf16_f32 v13, v227, v229
	v_cvt_pk_bf16_f32 v14, v230, v232
	v_cvt_pk_bf16_f32 v15, v231, v233
	s_waitcnt lgkmcnt(6)
	s_nop 0
	v_mfma_f32_32x32x16_bf16 v[64:79], v[112:115], v[12:15], v[64:79]
	s_waitcnt lgkmcnt(2)
	v_mfma_f32_32x32x16_bf16 v[48:63], v[116:119], v[12:15], v[48:63]
	s_waitcnt lgkmcnt(1)
	v_mfma_f32_32x32x16_bf16 v[32:47], v[120:123], v[12:15], v[32:47]
	v_exp_f32_e32 v123, v96
	ds_read_b64_tr_b16 v[96:97], v11 offset:32768
	ds_read_b64_tr_b16 v[98:99], v11 offset:34816
	v_pk_add_f32 v[120:121], v[2:3], v[2:3] op_sel_hi:[0,1]
	v_pk_add_f32 v[2:3], v[226:227], v[228:229]
	v_exp_f32_e32 v122, v105
	v_exp_f32_e32 v120, v110
	v_add_f32_e32 v105, v123, v225
	s_waitcnt lgkmcnt(2)
	v_mfma_f32_32x32x16_bf16 v[16:31], v[124:127], v[12:15], v[16:31]
	v_exp_f32_e32 v125, v100
	v_exp_f32_e32 v126, v101
	v_exp_f32_e32 v127, v102
	ds_read_b64_tr_b16 v[100:101], v11 offset:33280
	ds_read_b64_tr_b16 v[112:113], v11 offset:33792
	ds_read_b64_tr_b16 v[116:117], v11 offset:34304
	ds_read_b64_tr_b16 v[102:103], v11 offset:35328
	ds_read_b64_tr_b16 v[114:115], v11 offset:35840
	ds_read_b64_tr_b16 v[118:119], v11 offset:36352
	v_cvt_pk_bf16_f32 v12, v123, v225
	v_cvt_pk_bf16_f32 v13, v234, v235
	v_cvt_pk_bf16_f32 v14, v125, v126
	v_cvt_pk_bf16_f32 v15, v127, v236
	v_exp_f32_e32 v124, v107
	ds_read_b64_tr_b16 v[6:7], v11 offset:36864
	ds_read_b64_tr_b16 v[8:9], v11 offset:38912
	s_waitcnt lgkmcnt(8)
	v_mfma_f32_32x32x16_bf16 v[64:79], v[96:99], v[12:15], v[64:79]
	v_cvt_pk_bf16_f32 v5, v120, v0
	v_add_f32_e32 v123, v234, v235
	v_add_f32_e32 v107, v125, v126
	v_add_f32_e32 v125, v127, v236
	s_waitcnt lgkmcnt(4)
	v_mfma_f32_32x32x16_bf16 v[48:63], v[100:103], v[12:15], v[48:63]
	s_waitcnt lgkmcnt(3)
	v_mfma_f32_32x32x16_bf16 v[32:47], v[112:115], v[12:15], v[32:47]
	v_add_f32_e64 v112, v2, v2
	v_add_f32_e64 v113, v2, v3
	v_add_f32_e64 v2, v230, v232
	v_add_f32_e64 v3, v231, v233
	v_exp_f32_e32 v112, v108
	v_pk_add_f32 v[114:115], v[2:3], v[2:3] op_sel_hi:[0,1]
	v_exp_f32_e32 v114, v109
	v_cvt_pk_bf16_f32 v2, v104, v122
	v_cvt_pk_bf16_f32 v3, v106, v124
	s_waitcnt lgkmcnt(2)
	v_mfma_f32_32x32x16_bf16 v[16:31], v[116:119], v[12:15], v[16:31]
	ds_read_b64_tr_b16 v[12:13], v11 offset:37376
	ds_read_b64_tr_b16 v[96:97], v11 offset:37888
	ds_read_b64_tr_b16 v[100:101], v11 offset:38400
	ds_read_b64_tr_b16 v[14:15], v11 offset:39424
	ds_read_b64_tr_b16 v[98:99], v11 offset:39936
	ds_read_b64_tr_b16 v[102:103], v11 offset:40448
	v_cvt_pk_bf16_f32 v4, v112, v114
	s_waitcnt lgkmcnt(6)
	s_nop 0
	v_mfma_f32_32x32x16_bf16 v[64:79], v[6:9], v[2:5], v[64:79]
	v_add_f32_e64 v6, v104, v122
	v_add_f32_e64 v7, v105, v123
	v_add_f32_e64 v8, v106, v124
	v_add_f32_e64 v9, v107, v125
	v_add_f32_e64 v6, v6, v8
	v_add_f32_e64 v7, v7, v9
	v_pk_add_f32 v[8:9], v[112:113], v[114:115]
	s_waitcnt lgkmcnt(2)
	v_mfma_f32_32x32x16_bf16 v[48:63], v[12:15], v[2:5], v[48:63]
	v_add_f32_e64 v12, v120, v0
	v_add_f32_e64 v13, v121, v1
	v_add_f32_e64 v8, v8, v12
	v_add_f32_e64 v9, v9, v13
	v_add_f32_e64 v6, v6, v8
	v_add_f32_e64 v7, v7, v9
	v_add_f32_e32 v0, v6, v7
	s_waitcnt lgkmcnt(1)
	v_mfma_f32_32x32x16_bf16 v[32:47], v[96:99], v[2:5], v[32:47]
	v_add_f32_e32 v10, v10, v0
	s_waitcnt lgkmcnt(0)
	v_mfma_f32_32x32x16_bf16 v[16:31], v[100:103], v[2:5], v[16:31]
